# hgrn_local chunk bodies: per-item lane-constant row-store address parts in v240-255, one 64-bit add per store, cvt_pk rounding (32 VALU fewer per chunk)
# speedup vs baseline: 1.0015x; 1.0015x over previous
.LBB0_454:
	s_ashr_i32 s88, s61, 5
	s_ashr_i32 s89, s88, 31
	s_lshl_b32 s16, s61, 8
	s_lshl_b64 s[88:89], s[88:89], 11
	s_and_b32 s16, s16, 0x700
	s_or_b32 s88, s88, s16
	s_mul_i32 s16, s89, 0x1600
	s_mul_hi_u32 s33, s88, 0x1600
	s_add_i32 s33, s33, s16
	s_mul_i32 s16, s88, 0x1600
	s_add_u32 s90, s34, s16
	s_addc_u32 s33, s35, s33
	s_lshl_b32 s16, s61, 4
	s_and_b32 s92, s16, 0x180
	s_lshl_b32 s16, s92, 1
	s_add_u32 s90, s90, s16
	s_addc_u32 s91, s33, 0
	s_waitcnt vmcnt(10)
	v_mov_b32_e32 v129, v5
	v_mov_b32_e32 v115, v5
	v_lshl_add_u64 v[144:145], s[90:91], 0, v[128:129]
	s_waitcnt vmcnt(9)
	v_mov_b32_e32 v131, v5
	v_lshl_add_u64 v[142:143], s[90:91], 0, v[114:115]
	v_mov_b32_e32 v117, v5
	v_lshl_add_u64 v[14:15], v[144:145], 0, v[130:131]
	v_lshl_add_u64 v[12:13], v[142:143], 0, v[116:117]
	global_load_dwordx4 v[6:9], v[14:15], off offset:2048
	global_load_ushort v4, v[12:13], off offset:1024
	v_mov_b32_e32 v119, v5
	v_lshl_add_u64 v[10:11], v[142:143], 0, v[118:119]
	s_mov_b64 vcc, 0x1600
	v_lshl_add_u64 v[2:3], v[10:11], 0, vcc
	s_mov_b64 vcc, 0x2c00
	v_lshl_add_u64 v[16:17], v[10:11], 0, vcc
	v_mov_b32_e32 v121, v5
	v_lshl_add_u64 v[18:19], v[142:143], 0, v[120:121]
	v_mov_b32_e32 v123, v5
	v_lshl_add_u64 v[20:21], v[142:143], 0, v[122:123]
	v_mov_b32_e32 v125, v5
	v_lshl_add_u64 v[22:23], v[142:143], 0, v[124:125]
	v_mov_b32_e32 v127, v5
	v_lshl_add_u64 v[24:25], v[142:143], 0, v[126:127]
	v_lshl_add_u64 v[146:147], v[106:107], 0, s[16:17]
	s_movk_i32 s16, 0x2000
	global_load_ushort v41, v[10:11], off
	global_load_ushort v188, v[10:11], off offset:1024
	global_load_ushort v189, v[2:3], off offset:1024
	global_load_ushort v190, v[16:17], off offset:1024
	global_load_ushort v191, v[18:19], off offset:1024
	global_load_ushort v192, v[20:21], off offset:1024
	global_load_ushort v193, v[22:23], off offset:1024
	global_load_ushort v194, v[24:25], off offset:1024
	s_waitcnt vmcnt(8)
	v_lshlrev_b32_e32 v4, 16, v4
	v_add_f32_e32 v36, 0, v4
	s_waitcnt vmcnt(6)
	v_lshlrev_b32_e32 v4, 16, v188
	v_add_f32_e32 v40, v36, v4
	s_waitcnt vmcnt(5)
	v_lshlrev_b32_e32 v4, 16, v189
	v_add_f32_e32 v33, v40, v4
	s_waitcnt vmcnt(4)
	v_lshlrev_b32_e32 v4, 16, v190
	v_add_f32_e32 v32, v33, v4
	s_waitcnt vmcnt(3)
	v_lshlrev_b32_e32 v4, 16, v191
	v_add_f32_e32 v31, v32, v4
	s_waitcnt vmcnt(2)
	v_lshlrev_b32_e32 v4, 16, v192
	v_add_f32_e32 v30, v31, v4
	s_waitcnt vmcnt(1)
	v_lshlrev_b32_e32 v4, 16, v193
	v_add_f32_e32 v29, v30, v4
	s_waitcnt vmcnt(0)
	v_lshlrev_b32_e32 v4, 16, v194
	v_add_f32_e32 v27, v29, v4
	ds_bpermute_b32 v16, v91, v27
	ds_bpermute_b32 v34, v93, v27
	ds_bpermute_b32 v17, v95, v27
	ds_bpermute_b32 v35, v97, v27
	s_waitcnt lgkmcnt(3)
	v_cndmask_b32_e64 v4, v16, 0, s[4:5]
	s_waitcnt lgkmcnt(2)
	v_cndmask_b32_e64 v26, 0, v34, s[6:7]
	v_add_f32_e32 v4, v4, v26
	s_waitcnt lgkmcnt(1)
	v_cndmask_b32_e64 v26, 0, v17, s[8:9]
	v_add_f32_e32 v28, v4, v26
	s_waitcnt lgkmcnt(0)
	v_pk_add_f32 v[16:17], v[16:17], v[34:35]
	v_add_co_u32_e32 v34, vcc, s67, v10
	v_add_f32_e32 v26, v16, v17
	v_mul_f32_e32 v16, 0x3fb8aa3b, v28
	v_exp_f32_e32 v16, v16
	v_add_f32_e32 v17, v36, v28
	v_mul_f32_e32 v17, 0x3fb8aa3b, v17
	v_exp_f32_e32 v38, v17
	v_rcp_f32_e32 v16, v16
	v_addc_co_u32_e32 v35, vcc, 0, v11, vcc
	global_load_ushort v36, v[34:35], off offset:1536
	v_fma_f32 v17, -v16, v38, 1.0
	global_load_ushort v16, v[12:13], off
	v_add_co_u32_e32 v34, vcc, s16, v10
	v_rcp_f32_e32 v39, v38
	s_nop 0
	v_addc_co_u32_e32 v35, vcc, 0, v11, vcc
	global_load_ushort v35, v[34:35], off offset:3072
	s_nop 0
	global_load_ushort v37, v[18:19], off
	global_load_ushort v34, v[20:21], off
	s_nop 0
	global_load_ushort v23, v[22:23], off
	s_nop 0
	global_load_ushort v22, v[24:25], off
	v_mov_b32_e32 v19, s89
	v_mov_b32_e32 v25, s89
	v_or_b32_e32 v24, s88, v92
	v_lshlrev_b64 v[24:25], 10, v[24:25]
	v_lshl_add_u64 v[24:25], v[146:147], 0, v[24:25]
	v_mul_f32_e32 v4, 0x3fb8aa3b, v26
	v_exp_f32_e32 v4, v4
	s_waitcnt vmcnt(5)
	v_lshlrev_b32_e32 v16, 16, v16
	v_pk_mul_f32 v[16:17], v[38:39], v[16:17]
	s_waitcnt vmcnt(2)
	v_lshlrev_b32_e32 v34, 16, v34
	v_bfe_u32 v18, v16, 16, 1
	v_cvt_pk_bf16_f32 v38, v16, v17
	v_add3_u32 v16, v16, v18, s96
	v_or_b32_e32 v18, s88, v90
	v_lshlrev_b64 v[18:19], 10, v[18:19]
	v_lshl_add_u64 v[18:19], v[146:147], 0, v[18:19]
	ds_write_b16 v101, v38
	ds_write_b16_d16_hi v101, v38 offset:8832
	global_store_short_d16_hi v[18:19], v16, off
	v_add_f32_e32 v16, v40, v28
	v_mul_f32_e32 v16, 0x3fb8aa3b, v16
	v_exp_f32_e32 v20, v16
	v_lshlrev_b32_e32 v18, 16, v41
	v_or_b32_e32 v38, s88, v94
	s_waitcnt vmcnt(1)
; #define HG_LOAD_RAW(ch) do { _Pragma("unroll") for (int j = 0; j < 8; ++j) { const size_t t_ = (size_t)((ch) * 32 + 8 * part + j); rq[j] = pq[t_ * PW]; rf[j] = pf[t_ * PW]; } \
;         rv = *(const v4u*)(pv + (size_t)((ch) * 32 + vt_t) * PW); } while (0)
; #define HG_LOAD_RAW(ch) do { _Pragma("unroll") for (int j = 0; j < 8; ++j) { const size_t t_ = (size_t)((ch) * 32 + 8 * part + j); rq[j] = pq[t_ * PW]; rf[j] = pf[t_ * PW]; } \
;         rv = *(const v4u*)(pv + (size_t)((ch) * 32 + vt_t) * PW); } while (0)
; __device__ __forceinline__ void hgrn_local_ws2(Frame& F, int item) {
;     ...
;     HG_LOAD_RAW(0);
;     HG_ELEM(0);
;     HG_LOAD_RAW(1);
	v_lshlrev_b32_e32 v22, 16, v22
	v_rcp_f32_e32 v21, v20
	v_fma_f32 v19, -v20, v39, 1.0
	v_mov_b32_e32 v39, s89
	v_lshlrev_b64 v[38:39], 10, v[38:39]
	v_pk_mul_f32 v[18:19], v[20:21], v[18:19]
	v_lshlrev_b32_e32 v20, 16, v36
	v_cvt_pk_bf16_f32 v16, v18, v19
	ds_write_b16 v105, v16
	ds_write_b16_d16_hi v105, v16 offset:8832
	v_bfe_u32 v16, v18, 16, 1
	v_add3_u32 v16, v18, v16, s96
	global_store_short_d16_hi v[24:25], v16, off
	v_add_f32_e32 v16, v33, v28
	v_mul_f32_e32 v16, 0x3fb8aa3b, v16
	v_exp_f32_e32 v24, v16
	v_lshl_add_u64 v[38:39], v[146:147], 0, v[38:39]
	v_or_b32_e32 v36, s88, v98
	v_rcp_f32_e32 v25, v24
	v_fma_f32 v21, -v24, v21, 1.0
	v_pk_mul_f32 v[20:21], v[24:25], v[20:21]
	s_nop 0
	v_cvt_pk_bf16_f32 v16, v20, v21
	ds_write_b16 v157, v16
	ds_write_b16_d16_hi v157, v16 offset:8832
	v_bfe_u32 v16, v20, 16, 1
	v_add3_u32 v16, v20, v16, s96
	global_store_short_d16_hi v[38:39], v16, off
	v_add_f32_e32 v16, v32, v28
	v_mul_f32_e32 v16, 0x3fb8aa3b, v16
	v_exp_f32_e32 v32, v16
	v_lshlrev_b32_e32 v24, 16, v35
	v_mov_b32_e32 v39, s89
	v_or_b32_e32 v38, s88, v96
	v_rcp_f32_e32 v33, v32
	v_fma_f32 v25, -v32, v25, 1.0
	v_lshlrev_b64 v[38:39], 10, v[38:39]
	v_lshl_add_u64 v[38:39], v[146:147], 0, v[38:39]
	v_pk_mul_f32 v[24:25], v[32:33], v[24:25]
	v_lshlrev_b32_e32 v32, 16, v37
	v_cvt_pk_bf16_f32 v16, v24, v25
	ds_write_b16 v159, v16
	ds_write_b16_d16_hi v159, v16 offset:8832
	v_bfe_u32 v16, v24, 16, 1
	v_add3_u32 v16, v24, v16, s96
	global_store_short_d16_hi v[38:39], v16, off
	v_add_f32_e32 v16, v31, v28
	v_mul_f32_e32 v16, 0x3fb8aa3b, v16
	v_exp_f32_e32 v38, v16
	v_mov_b32_e32 v37, s89
	v_lshlrev_b64 v[36:37], 10, v[36:37]
	v_lshl_add_u64 v[36:37], v[146:147], 0, v[36:37]
	v_rcp_f32_e32 v39, v38
	v_fma_f32 v33, -v38, v33, 1.0
	v_mov_b32_e32 v24, v19
	v_mov_b32_e32 v20, v17
	v_pk_mul_f32 v[32:33], v[38:39], v[32:33]
	v_or_b32_e32 v38, s88, v102
	v_cvt_pk_bf16_f32 v16, v32, v33
	ds_write_b16 v161, v16
	ds_write_b16_d16_hi v161, v16 offset:8832
	v_bfe_u32 v16, v32, 16, 1
	v_add3_u32 v16, v32, v16, s96
	global_store_short_d16_hi v[36:37], v16, off
	v_add_f32_e32 v16, v30, v28
	v_mul_f32_e32 v16, 0x3fb8aa3b, v16
	v_exp_f32_e32 v30, v16
	v_mov_b32_e32 v37, s89
	v_or_b32_e32 v36, s88, v100
	v_lshlrev_b64 v[36:37], 10, v[36:37]
	v_rcp_f32_e32 v31, v30
	v_fma_f32 v35, -v30, v39, 1.0
	v_lshl_add_u64 v[36:37], v[146:147], 0, v[36:37]
	v_mov_b32_e32 v39, s89
	v_pk_mul_f32 v[34:35], v[30:31], v[34:35]
	v_lshlrev_b32_e32 v30, 16, v23
	v_cvt_pk_bf16_f32 v16, v34, v35
	ds_write_b16 v163, v16
	ds_write_b16_d16_hi v163, v16 offset:8832
	v_bfe_u32 v16, v34, 16, 1
	v_add3_u32 v16, v34, v16, s96
	global_store_short_d16_hi v[36:37], v16, off
	v_add_f32_e32 v16, v29, v28
	v_mul_f32_e32 v16, 0x3fb8aa3b, v16
	v_exp_f32_e32 v36, v16
	v_lshlrev_b64 v[38:39], 10, v[38:39]
	v_lshl_add_u64 v[38:39], v[146:147], 0, v[38:39]
	v_pk_mul_f32 v[18:19], v[4:5], v[24:25] op_sel_hi:[0,1]
	v_rcp_f32_e32 v37, v36
	v_fma_f32 v31, -v36, v31, 1.0
	v_pk_mul_f32 v[30:31], v[36:37], v[30:31]
	s_nop 0
	v_cvt_pk_bf16_f32 v16, v30, v31
	ds_write_b16 v165, v16
	ds_write_b16_d16_hi v165, v16 offset:8832
	v_bfe_u32 v16, v30, 16, 1
	v_add3_u32 v16, v30, v16, s96
	global_store_short_d16_hi v[38:39], v16, off
	v_add_f32_e32 v16, v27, v28
	v_mul_f32_e32 v16, 0x3fb8aa3b, v16
	v_exp_f32_e32 v28, v16
	v_mov_b32_e32 v30, v33
	v_bfe_u32 v27, v19, 16, 1
	v_add3_u32 v27, v19, v27, s96
	v_rcp_f32_e32 v29, v28
	v_fma_f32 v23, -v28, v37, 1.0
	v_pk_mul_f32 v[22:23], v[28:29], v[22:23]
	s_nop 0
	v_cvt_pk_bf16_f32 v16, v22, v23
	ds_write_b16 v167, v16
	ds_write_b16_d16_hi v167, v16 offset:8832
	v_bfe_u32 v16, v22, 16, 1
	v_mov_b32_e32 v29, s89
	v_or_b32_e32 v28, s88, v104
	v_add3_u32 v16, v22, v16, s96
	v_lshlrev_b64 v[28:29], 10, v[28:29]
	v_mov_b32_e32 v22, v35
	v_lshl_add_u64 v[28:29], v[146:147], 0, v[28:29]
	v_pk_mul_f32 v[22:23], v[4:5], v[22:23] op_sel_hi:[0,1]
	global_store_short_d16_hi v[28:29], v16, off
	v_pk_mul_f32 v[16:17], v[4:5], v[20:21] op_sel_hi:[0,1]
	v_pk_mul_f32 v[20:21], v[4:5], v[30:31] op_sel_hi:[0,1]
	v_bfe_u32 v24, v23, 16, 1
	v_bfe_u32 v25, v22, 16, 1
	v_bfe_u32 v28, v18, 16, 1
	v_add3_u32 v28, v18, v28, s96
	v_add3_u32 v18, v22, v25, s96
	v_add3_u32 v19, v23, v24, s96
	v_bfe_u32 v22, v16, 16, 1
	v_bfe_u32 v23, v17, 16, 1
	v_bfe_u32 v24, v20, 16, 1
	v_bfe_u32 v25, v21, 16, 1
	v_add3_u32 v21, v21, v25, s96
	v_add3_u32 v20, v20, v24, s96
	v_add3_u32 v17, v17, v23, s96
	v_add3_u32 v16, v16, v22, s96
	v_lshrrev_b32_e32 v16, 16, v16
	v_lshrrev_b32_e32 v17, 16, v17
	v_lshrrev_b32_e32 v20, 16, v20
	v_lshrrev_b32_e32 v21, 16, v21
	v_and_or_b32 v19, v19, s97, v21
	v_and_or_b32 v18, v18, s97, v20
	v_and_or_b32 v17, v27, s97, v17
	v_and_or_b32 v16, v28, s97, v16
	ds_write_b128 v169, v[16:19] offset:17664
	s_and_saveexec_b64 s[90:91], s[4:5]
	ds_write_b32 v174, v4 offset:39104
	s_or_b64 exec, exec, s[90:91]
	v_lshl_add_u64 v[16:17], v[12:13], 0, s[22:23]
	v_add_co_u32_e32 v12, vcc, s60, v12
	v_lshl_add_u64 v[18:19], v[10:11], 0, s[22:23]
	s_nop 0
	v_addc_co_u32_e32 v13, vcc, 0, v13, vcc
	v_add_co_u32_e32 v16, vcc, s60, v16
; #define LDS_BARRIER() do { asm volatile("s_waitcnt lgkmcnt(0)" ::: "memory"); __builtin_amdgcn_s_barrier(); asm volatile("" ::: "memory"); } while (0)
; #define HG_LOAD_RAW(ch) do { _Pragma("unroll") for (int j = 0; j < 8; ++j) { const size_t t_ = (size_t)((ch) * 32 + 8 * part + j); rq[j] = pq[t_ * PW]; rf[j] = pf[t_ * PW]; } \
;         rv = *(const v4u*)(pv + (size_t)((ch) * 32 + vt_t) * PW); } while (0)
; #define HG_LOAD_RAW(ch) do { _Pragma("unroll") for (int j = 0; j < 8; ++j) { const size_t t_ = (size_t)((ch) * 32 + 8 * part + j); rq[j] = pq[t_ * PW]; rf[j] = pf[t_ * PW]; } \
;         rv = *(const v4u*)(pv + (size_t)((ch) * 32 + vt_t) * PW); } while (0)
; __device__ __forceinline__ void hgrn_local_ws2(Frame& F, int item) {
;     ...
;     HG_LOAD_RAW(0);
;     HG_ELEM(0);
;     HG_LOAD_RAW(1);
;     LDS_BARRIER();
;     for (int ch = 0; ch < 8; ++ch) {
	v_lshl_add_u64 v[20:21], v[2:3], 0, s[22:23]
	s_nop 0
	v_addc_co_u32_e32 v17, vcc, 0, v17, vcc
	v_add_co_u32_e32 v10, vcc, s60, v10
	v_lshl_add_u64 v[22:23], v[142:143], 0, s[22:23]
	s_nop 0
	v_addc_co_u32_e32 v11, vcc, 0, v11, vcc
	v_add_co_u32_e32 v18, vcc, s60, v18
	v_mov_b32_e32 v133, v5
	s_nop 0
	v_addc_co_u32_e32 v19, vcc, 0, v19, vcc
	v_add_co_u32_e32 v2, vcc, s60, v2
	v_mov_b32_e32 v135, v5
	s_nop 0
	v_addc_co_u32_e32 v3, vcc, 0, v3, vcc
	v_add_co_u32_e32 v20, vcc, s60, v20
	v_lshl_add_u64 v[24:25], v[142:143], 0, v[132:133]
	s_nop 0
	v_addc_co_u32_e32 v21, vcc, 0, v21, vcc
	v_lshl_add_u64 v[28:29], v[22:23], 0, v[132:133]
	global_load_ushort v117, v[12:13], off
	global_load_ushort v119, v[16:17], off
	global_load_ushort v121, v[10:11], off
	global_load_ushort v123, v[18:19], off
	global_load_ushort v125, v[2:3], off
	global_load_ushort v127, v[20:21], off
	global_load_ushort v129, v[24:25], off
	global_load_ushort v131, v[28:29], off
	v_lshl_add_u64 v[2:3], v[142:143], 0, v[134:135]
	v_mov_b32_e32 v137, v5
	v_mov_b32_e32 v139, v5
	v_mov_b32_e32 v141, v5
	v_lshl_add_u64 v[10:11], v[22:23], 0, v[134:135]
	v_lshl_add_u64 v[12:13], v[142:143], 0, v[136:137]
	v_lshl_add_u64 v[16:17], v[22:23], 0, v[136:137]
	v_lshl_add_u64 v[18:19], v[142:143], 0, v[138:139]
	v_lshl_add_u64 v[20:21], v[22:23], 0, v[138:139]
	v_lshl_add_u64 v[24:25], v[142:143], 0, v[140:141]
	v_lshl_add_u64 v[22:23], v[22:23], 0, v[140:141]
	global_load_ushort v133, v[2:3], off
	global_load_ushort v135, v[10:11], off
	global_load_ushort v137, v[12:13], off
	global_load_ushort v139, v[16:17], off
	global_load_ushort v141, v[18:19], off
	global_load_ushort v187, v[20:21], off
	global_load_ushort v188, v[24:25], off
	global_load_ushort v189, v[22:23], off
	v_lshl_add_u64 v[14:15], v[14:15], 0, s[24:25]
	v_add_co_u32_e32 v2, vcc, 0x2c000, v14
	v_mov_b32_e32 v4, v5
	s_nop 0
	v_addc_co_u32_e32 v3, vcc, 0, v15, vcc
	global_load_dwordx4 v[70:73], v[2:3], off
	ds_write_b16 v173, v6 offset:27904
	ds_write_b16_d16_hi v173, v6 offset:27984
	ds_write_b16 v173, v7 offset:28064
	ds_write_b16_d16_hi v173, v7 offset:28144
	ds_write_b16 v173, v8 offset:28224
	ds_write_b16_d16_hi v173, v8 offset:28304
	ds_write_b16 v173, v9 offset:28384
	ds_write_b16_d16_hi v173, v9 offset:28464
	s_waitcnt lgkmcnt(0)
	s_barrier
	v_add_f32_e32 v115, 0, v26
	s_lshl_b32 s16, s92, 2
	v_mov_b32_e32 v2, v5
	v_mov_b32_e32 v3, v5
	v_mov_b64_e32 v[64:65], v[4:5]
	v_mov_b64_e32 v[68:69], v[4:5]
	v_mov_b64_e32 v[56:57], v[4:5]
	v_mov_b64_e32 v[60:61], v[4:5]
	v_mov_b64_e32 v[48:49], v[4:5]
	v_mov_b64_e32 v[52:53], v[4:5]
	v_mov_b64_e32 v[40:41], v[4:5]
	v_mov_b64_e32 v[44:45], v[4:5]
	v_mov_b64_e32 v[36:37], v[4:5]
	v_mov_b64_e32 v[32:33], v[4:5]
	v_mov_b64_e32 v[28:29], v[4:5]
	v_mov_b64_e32 v[24:25], v[4:5]
	v_mov_b64_e32 v[20:21], v[4:5]
	v_mov_b64_e32 v[16:17], v[4:5]
	v_mov_b64_e32 v[12:13], v[4:5]
	v_mov_b64_e32 v[8:9], v[4:5]
	s_mov_b32 s33, 0
	v_lshl_add_u64 v[148:149], v[110:111], 0, s[16:17]
	v_mov_b64_e32 v[62:63], v[2:3]
	v_mov_b64_e32 v[66:67], v[2:3]
	v_mov_b64_e32 v[54:55], v[2:3]
	v_mov_b64_e32 v[58:59], v[2:3]
	v_mov_b64_e32 v[46:47], v[2:3]
	v_mov_b64_e32 v[50:51], v[2:3]
	v_mov_b64_e32 v[38:39], v[2:3]
	v_mov_b64_e32 v[42:43], v[2:3]
	v_mov_b64_e32 v[34:35], v[2:3]
	v_mov_b64_e32 v[30:31], v[2:3]
	v_mov_b64_e32 v[26:27], v[2:3]
	v_mov_b64_e32 v[22:23], v[2:3]
	v_mov_b64_e32 v[18:19], v[2:3]
	v_mov_b64_e32 v[14:15], v[2:3]
	v_mov_b64_e32 v[10:11], v[2:3]
	v_mov_b64_e32 v[6:7], v[2:3]
	v_mov_b32_e32 v240, v90
	v_mov_b32_e32 v241, 0
	v_lshl_add_u64 v[240:241], s[88:89], 0, v[240:241]
	v_lshlrev_b64 v[240:241], 10, v[240:241]
	v_lshl_add_u64 v[240:241], v[146:147], 0, v[240:241]
	v_mov_b32_e32 v242, v92
	v_mov_b32_e32 v243, 0
	v_lshl_add_u64 v[242:243], s[88:89], 0, v[242:243]
	v_lshlrev_b64 v[242:243], 10, v[242:243]
	v_lshl_add_u64 v[242:243], v[146:147], 0, v[242:243]
	v_mov_b32_e32 v244, v94
	v_mov_b32_e32 v245, 0
	v_lshl_add_u64 v[244:245], s[88:89], 0, v[244:245]
	v_lshlrev_b64 v[244:245], 10, v[244:245]
	v_lshl_add_u64 v[244:245], v[146:147], 0, v[244:245]
	v_mov_b32_e32 v246, v96
	v_mov_b32_e32 v247, 0
	v_lshl_add_u64 v[246:247], s[88:89], 0, v[246:247]
	v_lshlrev_b64 v[246:247], 10, v[246:247]
	v_lshl_add_u64 v[246:247], v[146:147], 0, v[246:247]
	v_mov_b32_e32 v248, v98
	v_mov_b32_e32 v249, 0
	v_lshl_add_u64 v[248:249], s[88:89], 0, v[248:249]
	v_lshlrev_b64 v[248:249], 10, v[248:249]
	v_lshl_add_u64 v[248:249], v[146:147], 0, v[248:249]
	v_mov_b32_e32 v250, v100
	v_mov_b32_e32 v251, 0
	v_lshl_add_u64 v[250:251], s[88:89], 0, v[250:251]
	v_lshlrev_b64 v[250:251], 10, v[250:251]
	v_lshl_add_u64 v[250:251], v[146:147], 0, v[250:251]
	v_mov_b32_e32 v252, v102
	v_mov_b32_e32 v253, 0
	v_lshl_add_u64 v[252:253], s[88:89], 0, v[252:253]
	v_lshlrev_b64 v[252:253], 10, v[252:253]
	v_lshl_add_u64 v[252:253], v[146:147], 0, v[252:253]
	v_mov_b32_e32 v254, v104
	v_mov_b32_e32 v255, 0
	v_lshl_add_u64 v[254:255], s[88:89], 0, v[254:255]
	v_lshlrev_b64 v[254:255], 10, v[254:255]
	v_lshl_add_u64 v[254:255], v[146:147], 0, v[254:255]
	s_branch .LBB0_459

.LBB0_462:
	s_waitcnt vmcnt(15)
	v_lshlrev_b32_e32 v2, 16, v119
	v_add_f32_e32 v4, 0, v2
	s_waitcnt vmcnt(13)
	v_lshlrev_b32_e32 v2, 16, v123
	v_add_f32_e32 v80, v4, v2
	s_waitcnt vmcnt(11)
	v_lshlrev_b32_e32 v2, 16, v127
	v_add_f32_e32 v82, v80, v2
	s_waitcnt vmcnt(9)
	v_lshlrev_b32_e32 v2, 16, v131
	v_add_f32_e32 v84, v82, v2
	s_waitcnt vmcnt(7)
	v_lshlrev_b32_e32 v2, 16, v135
	v_add_f32_e32 v86, v84, v2
	s_waitcnt vmcnt(5)
	v_lshlrev_b32_e32 v2, 16, v139
	v_add_f32_e32 v88, v86, v2
	s_waitcnt vmcnt(3)
	v_lshlrev_b32_e32 v2, 16, v187
	v_add_f32_e32 v150, v88, v2
	s_waitcnt vmcnt(1)
	v_lshlrev_b32_e32 v2, 16, v189
	v_add_f32_e32 v152, v150, v2
	ds_bpermute_b32 v2, v91, v152
	ds_bpermute_b32 v74, v93, v152
	ds_bpermute_b32 v3, v95, v152
	ds_bpermute_b32 v75, v97, v152
	s_add_i32 s92, s33, 1
	s_waitcnt lgkmcnt(3)
	v_cndmask_b32_e64 v76, v2, 0, s[4:5]
	s_waitcnt lgkmcnt(2)
	v_cndmask_b32_e64 v77, 0, v74, s[6:7]
	v_add_f32_e32 v76, v76, v77
	s_waitcnt lgkmcnt(1)
	v_cndmask_b32_e64 v77, 0, v3, s[8:9]
	v_add_f32_e32 v153, v76, v77
	s_waitcnt lgkmcnt(0)
	v_pk_add_f32 v[2:3], v[2:3], v[74:75]
	v_mul_f32_e32 v74, 0x3fb8aa3b, v153
	v_add_f32_e32 v4, v4, v153
	v_exp_f32_e32 v74, v74
	v_mul_f32_e32 v4, 0x3fb8aa3b, v4
	v_exp_f32_e32 v76, v4
	v_add_f32_e32 v3, v2, v3
	v_rcp_f32_e32 v74, v74
	v_mul_f32_e32 v2, 0x3fb8aa3b, v115
	v_rcp_f32_e32 v77, v76
	s_bitcmp1_b32 s92, 0
	v_exp_f32_e32 v154, v2
	s_cselect_b32 s16, 0x9ac0, 0
	v_fma_f32 v75, -v74, v76, 1.0
	v_lshlrev_b32_e32 v74, 16, v117
	s_add_i32 s16, s16, 0
	v_pk_mul_f32 v[74:75], v[76:77], v[74:75]
	v_lshl_add_u32 v76, v99, 1, s16
	v_cvt_pk_bf16_f32 v4, v74, v75
	ds_write_b16 v76, v4
	ds_write_b16_d16_hi v76, v4 offset:8832
	v_mul_f32_e32 v4, v154, v74
	s_lshl_b32 s92, s92, 5
	v_cvt_pk_bf16_f32 v74, v4, v4
	s_lshl_b32 s98, s92, 10
	s_mov_b32 s99, 0
	v_lshl_add_u64 v[78:79], v[240:241], 0, s[98:99]
	v_add_f32_e32 v4, v80, v153
	v_mul_f32_e32 v4, 0x3fb8aa3b, v4
	global_store_short_d16_hi v[78:79], v74, off
	v_exp_f32_e32 v78, v4
	v_lshlrev_b32_e32 v76, 16, v121
	v_lshl_add_u32 v74, v103, 1, s16
	v_mul_f32_e32 v2, 0x3fb8aa3b, v3
	v_rcp_f32_e32 v79, v78
	v_fma_f32 v77, -v78, v77, 1.0
	v_exp_f32_e32 v2, v2
	v_pk_mul_f32 v[76:77], v[78:79], v[76:77]
	s_nop 0
	v_cvt_pk_bf16_f32 v4, v76, v77
	ds_write_b16 v74, v4
	ds_write_b16_d16_hi v74, v4 offset:8832
	v_mul_f32_e32 v4, v154, v76
	v_cvt_pk_bf16_f32 v74, v4, v4
	v_lshl_add_u64 v[80:81], v[242:243], 0, s[98:99]
	v_add_f32_e32 v4, v82, v153
	v_mul_f32_e32 v4, 0x3fb8aa3b, v4
	global_store_short_d16_hi v[80:81], v74, off
	v_exp_f32_e32 v80, v4
	v_lshlrev_b32_e32 v78, 16, v125
	v_lshl_add_u32 v74, v156, 1, s16
	v_rcp_f32_e32 v81, v80
	v_fma_f32 v79, -v80, v79, 1.0
	v_pk_mul_f32 v[78:79], v[80:81], v[78:79]
	s_nop 0
	v_cvt_pk_bf16_f32 v4, v78, v79
	ds_write_b16 v74, v4
	ds_write_b16_d16_hi v74, v4 offset:8832
	v_mul_f32_e32 v4, v154, v78
	v_cvt_pk_bf16_f32 v74, v4, v4
	v_lshl_add_u64 v[82:83], v[244:245], 0, s[98:99]
	v_add_f32_e32 v4, v84, v153
	v_mul_f32_e32 v4, 0x3fb8aa3b, v4
	global_store_short_d16_hi v[82:83], v74, off
	v_exp_f32_e32 v82, v4
	v_lshlrev_b32_e32 v80, 16, v129
	v_lshl_add_u32 v74, v158, 1, s16
	v_mov_b32_e32 v78, v75
	v_rcp_f32_e32 v83, v82
	v_fma_f32 v81, -v82, v81, 1.0
	v_pk_mul_f32 v[80:81], v[82:83], v[80:81]
	s_nop 0
	v_cvt_pk_bf16_f32 v4, v80, v81
	ds_write_b16 v74, v4
	ds_write_b16_d16_hi v74, v4 offset:8832
	v_mul_f32_e32 v4, v154, v80
	v_cvt_pk_bf16_f32 v74, v4, v4
	v_lshl_add_u64 v[84:85], v[246:247], 0, s[98:99]
	v_add_f32_e32 v4, v86, v153
	v_mul_f32_e32 v4, 0x3fb8aa3b, v4
	global_store_short_d16_hi v[84:85], v74, off
	v_exp_f32_e32 v84, v4
	v_lshlrev_b32_e32 v82, 16, v133
	v_lshl_add_u32 v74, v160, 1, s16
	v_mov_b32_e32 v80, v77
	v_rcp_f32_e32 v85, v84
	v_fma_f32 v83, -v84, v83, 1.0
	v_pk_mul_f32 v[76:77], v[2:3], v[80:81] op_sel_hi:[0,1]
	v_pk_mul_f32 v[82:83], v[84:85], v[82:83]
	s_nop 0
	v_cvt_pk_bf16_f32 v4, v82, v83
	ds_write_b16 v74, v4
	ds_write_b16_d16_hi v74, v4 offset:8832
	v_mul_f32_e32 v4, v154, v82
	v_cvt_pk_bf16_f32 v74, v4, v4
	v_lshl_add_u64 v[86:87], v[248:249], 0, s[98:99]
	v_add_f32_e32 v4, v88, v153
	v_mul_f32_e32 v4, 0x3fb8aa3b, v4
	global_store_short_d16_hi v[86:87], v74, off
	v_exp_f32_e32 v86, v4
	v_lshlrev_b32_e32 v84, 16, v137
	v_lshl_add_u32 v74, v162, 1, s16
	v_rcp_f32_e32 v87, v86
	v_fma_f32 v85, -v86, v85, 1.0
	v_pk_mul_f32 v[84:85], v[86:87], v[84:85]
	s_nop 0
	v_cvt_pk_bf16_f32 v4, v84, v85
	ds_write_b16 v74, v4
	ds_write_b16_d16_hi v74, v4 offset:8832
	v_mul_f32_e32 v4, v154, v84
	v_cvt_pk_bf16_f32 v74, v4, v4
	v_lshl_add_u64 v[88:89], v[250:251], 0, s[98:99]
	v_add_f32_e32 v4, v150, v153
	v_mul_f32_e32 v4, 0x3fb8aa3b, v4
	global_store_short_d16_hi v[88:89], v74, off
	v_exp_f32_e32 v88, v4
	v_lshlrev_b32_e32 v86, 16, v141
	v_lshl_add_u32 v74, v164, 1, s16
	v_bfe_u32 v84, v76, 16, 1
	v_rcp_f32_e32 v89, v88
	v_fma_f32 v87, -v88, v87, 1.0
	v_add3_u32 v84, v76, v84, s96
	v_pk_mul_f32 v[86:87], v[88:89], v[86:87]
	s_nop 0
	v_cvt_pk_bf16_f32 v4, v86, v87
	ds_write_b16 v74, v4
	ds_write_b16_d16_hi v74, v4 offset:8832
	v_mul_f32_e32 v4, v154, v86
	v_cvt_pk_bf16_f32 v74, v4, v4
	v_lshl_add_u64 v[150:151], v[252:253], 0, s[98:99]
	v_add_f32_e32 v4, v152, v153
	v_mul_f32_e32 v4, 0x3fb8aa3b, v4
	global_store_short_d16_hi v[150:151], v74, off
	v_exp_f32_e32 v150, v4
	v_lshlrev_b32_e32 v88, 16, v188
	v_lshl_add_u32 v74, v166, 1, s16
	v_mov_b32_e32 v86, v83
	v_rcp_f32_e32 v151, v150
	v_fma_f32 v89, -v150, v89, 1.0
	v_bfe_u32 v83, v77, 16, 1
	v_add3_u32 v83, v77, v83, s96
	v_pk_mul_f32 v[88:89], v[150:151], v[88:89]
	s_nop 0
	v_cvt_pk_bf16_f32 v4, v88, v89
	ds_write_b16 v74, v4
	ds_write_b16_d16_hi v74, v4 offset:8832
	v_mul_f32_e32 v4, v154, v88
	v_cvt_pk_bf16_f32 v74, v4, v4
	v_lshl_add_u64 v[150:151], v[254:255], 0, s[98:99]
	v_mov_b32_e32 v88, v85
	v_pk_mul_f32 v[80:81], v[2:3], v[88:89] op_sel_hi:[0,1]
	global_store_short_d16_hi v[150:151], v74, off
	v_pk_mul_f32 v[74:75], v[2:3], v[78:79] op_sel_hi:[0,1]
	v_pk_mul_f32 v[78:79], v[2:3], v[86:87] op_sel_hi:[0,1]
	v_bfe_u32 v82, v80, 16, 1
	v_bfe_u32 v4, v81, 16, 1
	v_add3_u32 v76, v80, v82, s96
	v_bfe_u32 v82, v79, 16, 1
	v_add3_u32 v4, v81, v4, s96
	v_bfe_u32 v77, v74, 16, 1
	v_bfe_u32 v80, v75, 16, 1
	v_bfe_u32 v81, v78, 16, 1
	v_add3_u32 v79, v79, v82, s96
	v_add3_u32 v78, v78, v81, s96
	v_add3_u32 v75, v75, v80, s96
	v_add3_u32 v74, v74, v77, s96
	v_lshrrev_b32_e32 v77, 16, v79
	v_lshrrev_b32_e32 v74, 16, v74
	v_lshrrev_b32_e32 v75, 16, v75
	v_lshrrev_b32_e32 v78, 16, v78
	v_and_or_b32 v77, v4, s97, v77
	v_lshl_add_u32 v4, v168, 1, s16
	v_and_or_b32 v76, v76, s97, v78
	v_and_or_b32 v75, v83, s97, v75
	v_and_or_b32 v74, v84, s97, v74
	v_lshl_add_u32 v78, v90, 1, v4
	ds_write_b128 v78, v[74:77] offset:17664
	s_and_saveexec_b64 s[92:93], s[4:5]
	v_add_u32_e32 v4, v4, v183
	ds_write_b32 v4, v2 offset:39104
	s_or_b64 exec, exec, s[92:93]
	v_add_u32_e32 v2, s16, v170
	v_add3_u32 v2, v2, v171, v172
	s_cmp_gt_u32 s33, 5
	s_waitcnt vmcnt(8)
	ds_write_b16 v2, v70 offset:27904
	ds_write_b16_d16_hi v2, v70 offset:27984
	ds_write_b16 v2, v71 offset:28064
	ds_write_b16_d16_hi v2, v71 offset:28144
	ds_write_b16 v2, v72 offset:28224
	ds_write_b16_d16_hi v2, v72 offset:28304
	ds_write_b16 v2, v73 offset:28384
	ds_write_b16_d16_hi v2, v73 offset:28464
	s_cbranch_scc1 .LBB0_466
	s_lshl_b32 s16, s33, 5
	s_add_i32 s16, s16, 64
	v_or_b32_e32 v2, s16, v90
	v_mul_lo_u32 v4, v2, s63
	v_lshl_add_u64 v[70:71], v[4:5], 1, v[142:143]
	v_add_co_u32_e32 v72, vcc, 0x1000, v70
	global_load_ushort v117, v[70:71], off
	global_load_ushort v119, v[70:71], off offset:1024
	v_addc_co_u32_e32 v73, vcc, 0, v71, vcc
	global_load_ushort v121, v[72:73], off offset:1536
	global_load_ushort v123, v[72:73], off offset:2560
	v_add_co_u32_e32 v72, vcc, 0x2000, v70
	v_or_b32_e32 v2, s16, v1
	s_nop 0
	v_addc_co_u32_e32 v73, vcc, 0, v71, vcc
	global_load_ushort v125, v[72:73], off offset:3072
	v_add_co_u32_e32 v72, vcc, 0x3000, v70
	v_mul_lo_u32 v4, v2, s63
	s_nop 0
	v_addc_co_u32_e32 v73, vcc, 0, v71, vcc
	global_load_ushort v127, v[72:73], off
	v_add_co_u32_e32 v72, vcc, 0x4000, v70
	s_nop 1
	v_addc_co_u32_e32 v73, vcc, 0, v71, vcc
	global_load_ushort v129, v[72:73], off offset:512
	global_load_ushort v131, v[72:73], off offset:1536
	v_add_co_u32_e32 v72, vcc, 0x5000, v70
	s_nop 1
	v_addc_co_u32_e32 v73, vcc, 0, v71, vcc
	global_load_ushort v133, v[72:73], off offset:2048
	global_load_ushort v135, v[72:73], off offset:3072
	v_add_co_u32_e32 v72, vcc, 0x6000, v70
	s_nop 1
	v_addc_co_u32_e32 v73, vcc, 0, v71, vcc
	global_load_ushort v137, v[72:73], off offset:3584
	v_add_co_u32_e32 v72, vcc, 0x7000, v70
	s_nop 1
	v_addc_co_u32_e32 v73, vcc, 0, v71, vcc
	global_load_ushort v139, v[72:73], off offset:512
	v_add_co_u32_e32 v72, vcc, 0x8000, v70
	s_nop 1
	v_addc_co_u32_e32 v73, vcc, 0, v71, vcc
	v_add_co_u32_e32 v70, vcc, 0x9000, v70
	global_load_ushort v141, v[72:73], off offset:1024
	global_load_ushort v187, v[72:73], off offset:2048
	v_addc_co_u32_e32 v71, vcc, 0, v71, vcc
	global_load_ushort v188, v[70:71], off offset:2560
	global_load_ushort v189, v[70:71], off offset:3584
	v_lshl_add_u64 v[70:71], v[4:5], 1, v[144:145]
	global_load_dwordx4 v[70:73], v[70:71], off offset:2048

; #define LAS __attribute__((address_space(3)))
; #define MFMA16(a, b, c) __builtin_amdgcn_mfma_f32_16x16x32_bf16((a), (b), (c), 0, 0, 0)
; __device__ __forceinline__ void hgrn_local_ws2(Frame& F, int item) {
;     ...
;             const LAS unsigned char* bb = F.lds + (ch & 1) * HB_BYTES;
;             const LAS bf16* QD = (const LAS bf16*)(bb + HB_QD); const LAS bf16* KH = (const LAS bf16*)(bb + HB_KH); const LAS bf16* KDT = (const LAS bf16*)(bb + HB_KDT);
;             const LAS bf16* VT = (const LAS bf16*)(bb + HB_VT); const LAS float* DEC = (const LAS float*)(bb + HB_DEC);
;             f32x4 T00 = (f32x4){0.f, 0.f, 0.f, 0.f}, T01 = T00, T11 = T00;
; #pragma unroll
;             for (int kk = 0; kk < 4; ++kk) {
;                 const bf16x8 kh0 = *(const LAS bf16x8*)(KH + QDOFF(l15) + 32 * kk + 8 * quad), kh1 = *(const LAS bf16x8*)(KH + QDOFF(16 + l15) + 32 * kk + 8 * quad);
;                 const bf16x8 q0 = *(const LAS bf16x8*)(QD + QDOFF(l15) + 32 * kk + 8 * quad), q1 = *(const LAS bf16x8*)(QD + QDOFF(16 + l15) + 32 * kk + 8 * quad);
;                 T00 = MFMA16(kh0, q0, T00); T01 = MFMA16(kh0, q1, T01); T11 = MFMA16(kh1, q1, T11);
;             }
; #pragma unroll
;             for (int r = 0; r < 4; ++r) { if (4 * quad + r > l15) { T00[r] = 0.f; T11[r] = 0.f; } }
;             const bf16x8 a0 = pack8(T00, (f32x4){0.f, 0.f, 0.f, 0.f}), a1 = pack8(T01, T11);
;             f32x4 O[2][2];
; #pragma unroll
;             for (int g = 0; g < 2; ++g) { O[g][0] = (f32x4){0.f, 0.f, 0.f, 0.f}; O[g][1] = O[g][0]; }
; #pragma unroll
;             for (int kk = 0; kk < 4; ++kk) {
;                 const bf16x8 aq0 = join8(*(const LAS v2u*)(QD + QDOFF(l15) + 32 * kk + 4 * quad), *(const LAS v2u*)(QD + QDOFF(l15) + 32 * kk + 16 + 4 * quad));
;                 const bf16x8 aq1 = join8(*(const LAS v2u*)(QD + QDOFF(16 + l15) + 32 * kk + 4 * quad), *(const LAS v2u*)(QD + QDOFF(16 + l15) + 32 * kk + 16 + 4 * quad));
; #pragma unroll
;                 for (int g = 0; g < 2; ++g) { const bf16x8 bs = pack8(S[g][2 * kk], S[g][2 * kk + 1]); O[g][0] = MFMA16(aq0, bs, O[g][0]); O[g][1] = MFMA16(aq1, bs, O[g][1]); }
;             }
.LBB0_468:
	s_bitcmp1_b32 s33, 0
	s_cselect_b32 s16, 0x9ac0, 0
	s_add_i32 s92, s16, 0
	v_lshl_add_u32 v207, v176, 1, s92
	v_lshl_add_u32 v2, v175, 1, v207
	ds_read_b128 v[74:77], v2 offset:8832
	ds_read_b128 v[78:81], v2
	v_lshl_add_u32 v3, v177, 1, v207
	ds_read_b128 v[82:85], v3 offset:8832
	ds_read_b128 v[86:89], v3
	ds_read_b128 v[150:153], v2 offset:8896
	ds_read_b128 v[190:193], v2 offset:64
	ds_read_b128 v[194:197], v3 offset:8896
	ds_read_b128 v[198:201], v3 offset:64
	s_waitcnt lgkmcnt(6)
	v_mfma_f32_16x16x32_bf16 v[78:81], v[74:77], v[78:81], 0
	v_add_u32_e32 v217, v2, v184
	v_add_u32_e32 v218, v3, v184
	s_lshl_b32 s16, s33, 5
	s_waitcnt lgkmcnt(4)
	v_mfma_f32_16x16x32_bf16 v[82:85], v[82:85], v[86:89], 0
	s_mov_b32 s93, 0x8000
	s_waitcnt lgkmcnt(2)
	v_mfma_f32_16x16x32_bf16 v[78:81], v[150:153], v[190:193], v[78:81]
	ds_read_b128 v[190:193], v2 offset:8960
	ds_read_b128 v[202:205], v2 offset:128
	s_waitcnt lgkmcnt(2)
	v_mfma_f32_16x16x32_bf16 v[82:85], v[194:197], v[198:201], v[82:85]
	ds_read_b128 v[194:197], v3 offset:8960
	ds_read_b128 v[208:211], v3 offset:128
	s_waitcnt lgkmcnt(2)
	v_mfma_f32_16x16x32_bf16 v[78:81], v[190:193], v[202:205], v[78:81]
	ds_read_b128 v[202:205], v3 offset:9024
	ds_read_b128 v[212:215], v3 offset:192
	s_waitcnt lgkmcnt(2)
	v_mfma_f32_16x16x32_bf16 v[82:85], v[194:197], v[208:211], v[82:85]
	ds_read_b128 v[194:197], v2 offset:9024
	s_waitcnt lgkmcnt(1)
	v_mfma_f32_16x16x32_bf16 v[82:85], v[202:205], v[212:215], v[82:85]
	ds_read_b128 v[202:205], v2 offset:192
	v_mfma_f32_16x16x32_bf16 v[74:77], v[74:77], v[86:89], 0
	v_cvt_pk_bf16_f32 v86, v62, v63
	s_nop 4
	v_cndmask_b32_e64 v4, v85, 0, s[10:11]
	v_cndmask_b32_e64 v154, v84, 0, s[12:13]
	s_waitcnt lgkmcnt(0)
	v_mfma_f32_16x16x32_bf16 v[78:81], v[194:197], v[202:205], v[78:81]
	v_cndmask_b32_e64 v155, v83, 0, s[0:1]
	v_cndmask_b32_e64 v216, v82, 0, s[86:87]
	ds_read2_b64 v[82:85], v218 offset1:4
	v_mfma_f32_16x16x32_bf16 v[74:77], v[150:153], v[198:201], v[74:77]
	v_cvt_pk_bf16_f32 v87, v64, v65
	s_nop 2
	v_cndmask_b32_e64 v202, v81, 0, s[10:11]
	v_cndmask_b32_e64 v203, v80, 0, s[12:13]
	v_cndmask_b32_e64 v204, v79, 0, s[0:1]
	v_cndmask_b32_e64 v198, v78, 0, s[86:87]
	ds_read2_b64 v[78:81], v217 offset1:4
	v_mfma_f32_16x16x32_bf16 v[74:77], v[190:193], v[208:211], v[74:77]
	v_cvt_pk_bf16_f32 v2, v198, v204
	ds_read2_b64 v[198:201], v218 offset0:8 offset1:12
	v_cvt_pk_bf16_f32 v88, v66, v67
	v_mfma_f32_16x16x32_bf16 v[74:77], v[194:197], v[212:215], v[74:77]
	ds_read2_b64 v[194:197], v217 offset0:8 offset1:12
	v_cvt_pk_bf16_f32 v89, v68, v69
	v_cvt_pk_bf16_f32 v190, v34, v35
	v_cvt_pk_bf16_f32 v191, v36, v37
	s_waitcnt lgkmcnt(2)
	v_mfma_f32_16x16x32_bf16 v[150:153], v[78:81], v[86:89], 0
	v_cvt_pk_bf16_f32 v192, v30, v31
	v_cvt_pk_bf16_f32 v193, v32, v33
	v_cvt_pk_bf16_f32 v3, v203, v202
	v_mfma_f32_16x16x32_bf16 v[86:89], v[82:85], v[86:89], 0
	v_cvt_pk_bf16_f32 v202, v54, v55
	v_cvt_pk_bf16_f32 v203, v56, v57
	v_cvt_pk_bf16_f32 v204, v58, v59
	v_mfma_f32_16x16x32_bf16 v[78:81], v[78:81], v[190:193], 0
	v_cvt_pk_bf16_f32 v205, v60, v61
	v_cvt_pk_bf16_f32 v208, v46, v47
	v_cvt_pk_bf16_f32 v209, v48, v49
	v_mfma_f32_16x16x32_bf16 v[82:85], v[82:85], v[190:193], 0
	v_cvt_pk_bf16_f32 v190, v26, v27
	v_cvt_pk_bf16_f32 v191, v28, v29
	v_cvt_pk_bf16_f32 v192, v22, v23
	s_waitcnt lgkmcnt(0)
	v_mfma_f32_16x16x32_bf16 v[150:153], v[194:197], v[202:205], v[150:153]
	v_cvt_pk_bf16_f32 v193, v24, v25
	v_cvt_pk_bf16_f32 v210, v50, v51
	v_cvt_pk_bf16_f32 v211, v52, v53
	v_mfma_f32_16x16x32_bf16 v[86:89], v[198:201], v[202:205], v[86:89]
	ds_read2_b64 v[202:205], v217 offset0:16 offset1:20
	v_cvt_pk_bf16_f32 v74, v74, v75
	v_cvt_pk_bf16_f32 v75, v76, v77
	v_mfma_f32_16x16x32_bf16 v[78:81], v[194:197], v[190:193], v[78:81]
	ds_read2_b64 v[194:197], v218 offset0:16 offset1:20
	v_cvt_pk_bf16_f32 v77, v154, v4
	v_add_u32_e32 v154, s92, v179
	v_mfma_f32_16x16x32_bf16 v[82:85], v[198:201], v[190:193], v[82:85]
	ds_read2_b64 v[198:201], v217 offset0:24 offset1:28
	v_cvt_pk_bf16_f32 v190, v18, v19
	v_cvt_pk_bf16_f32 v191, v20, v21
	v_cvt_pk_bf16_f32 v192, v14, v15
	v_cvt_pk_bf16_f32 v193, v16, v17
	s_waitcnt lgkmcnt(2)
	v_mfma_f32_16x16x32_bf16 v[150:153], v[202:205], v[208:211], v[150:153]
	v_mov_b32_e32 v4, v5
	v_cvt_pk_bf16_f32 v76, v216, v155
	v_mov_b32_e32 v155, v5
	v_mfma_f32_16x16x32_bf16 v[78:81], v[202:205], v[190:193], v[78:81]
	ds_read2_b64 v[202:205], v218 offset0:24 offset1:28
	s_waitcnt lgkmcnt(2)
	v_mfma_f32_16x16x32_bf16 v[86:89], v[194:197], v[208:211], v[86:89]
	v_cvt_pk_bf16_f32 v208, v38, v39
	v_cvt_pk_bf16_f32 v209, v40, v41
	v_cvt_pk_bf16_f32 v210, v42, v43
	v_mfma_f32_16x16x32_bf16 v[82:85], v[194:197], v[190:193], v[82:85]
	v_cvt_pk_bf16_f32 v211, v44, v45
	v_cvt_pk_bf16_f32 v190, v10, v11
	v_cvt_pk_bf16_f32 v191, v12, v13
	v_cvt_pk_bf16_f32 v192, v6, v7
	v_cvt_pk_bf16_f32 v193, v8, v9
	s_waitcnt lgkmcnt(1)
	v_mfma_f32_16x16x32_bf16 v[150:153], v[198:201], v[208:211], v[150:153]
	v_mfma_f32_16x16x32_bf16 v[78:81], v[198:201], v[190:193], v[78:81]
	v_lshlrev_b32_e32 v198, 1, v178
	v_add3_u32 v199, v154, v185, v198
	v_add_u32_e32 v154, 0x6800, v199
	ds_read2_b64 v[194:197], v154 offset0:160 offset1:164
	s_waitcnt lgkmcnt(1)
	v_mfma_f32_16x16x32_bf16 v[86:89], v[202:205], v[208:211], v[86:89]
	v_or_b32_e32 v154, s16, v178
	v_mfma_f32_16x16x32_bf16 v[82:85], v[202:205], v[190:193], v[82:85]
	s_waitcnt lgkmcnt(0)
; #define LAS __attribute__((address_space(3)))
; #define MFMA16(a, b, c) __builtin_amdgcn_mfma_f32_16x16x32_bf16((a), (b), (c), 0, 0, 0)
; __device__ __forceinline__ void hgrn_local_ws2(Frame& F, int item) {
;     ...
; #pragma unroll
;             for (int g = 0; g < 2; ++g) {
;                 const LAS bf16* vrow = VT + VTOFF(32 * w + 16 * g + l15);
;                 const bf16x8 bv = join8(*(const LAS v2u*)(vrow + 4 * quad), *(const LAS v2u*)(vrow + 16 + 4 * quad));
;                 O[g][0] = MFMA16(a0, bv, O[g][0]); O[g][1] = MFMA16(a1, bv, O[g][1]);
;                 float* op = F.OLOC + (row0 + (size_t)(ch * 32 + 4 * quad)) * 512 + h * 128 + 32 * w + 16 * g + l15;
; #pragma unroll
;                 for (int r = 0; r < 4; ++r) { op[(size_t)r * 512] = O[g][0][r]; op[(size_t)(16 + r) * 512] = O[g][1][r]; }
;             }
;             const bf16x8 bvn0 = *(const LAS bf16x8*)(VT + VTOFF(32 * w + l15) + 8 * quad), bvn1 = *(const LAS bf16x8*)(VT + VTOFF(32 * w + 16 + l15) + 8 * quad);
; #pragma unroll
;             for (int tc = 0; tc < 8; ++tc) {
;                 const f32x4 dec = *(const LAS f32x4*)(DEC + 16 * tc + 4 * quad);
;                 const bf16x8 ak = *(const LAS bf16x8*)(KDT + (16 * tc + l15) * KT_STRIDE + 8 * quad);
;                 S[0][tc] = S[0][tc] * dec; S[1][tc] = S[1][tc] * dec;
;                 S[0][tc] = MFMA16(ak, bvn0, S[0][tc]); S[1][tc] = MFMA16(ak, bvn1, S[1][tc]);
;             }
	v_mfma_f32_16x16x32_bf16 v[190:193], v[2:5], v[194:197], v[150:153]
	s_nop 2
	v_lshl_add_u64 v[150:151], s[88:89], 0, v[154:155]
	v_lshlrev_b64 v[150:151], 11, v[150:151]
	v_lshl_add_u64 v[208:209], v[148:149], 0, v[150:151]
	v_mfma_f32_16x16x32_bf16 v[86:89], v[74:77], v[194:197], v[86:89]
	v_add_co_u32_e32 v154, vcc, s93, v208
	s_mov_b32 s93, 0x9000
	s_nop 0
	v_addc_co_u32_e32 v155, vcc, 0, v209, vcc
	v_add_co_u32_e32 v150, vcc, s93, v208
	global_store_dword v[208:209], v190, off
	s_nop 0
	v_addc_co_u32_e32 v151, vcc, 0, v209, vcc
	global_store_dword v[150:151], v86, off offset:-4096
	global_store_dword v[208:209], v191, off offset:2048
	global_store_dword v[154:155], v87, off offset:2048
	v_add_u32_e32 v86, s92, v180
	v_add3_u32 v198, v86, v186, v198
	v_add_u32_e32 v86, 0x6800, v198
	ds_read2_b64 v[194:197], v86 offset0:160 offset1:164
	v_add_co_u32_e32 v152, vcc, s67, v208
	s_waitcnt lgkmcnt(0)
	v_mfma_f32_16x16x32_bf16 v[78:81], v[2:5], v[194:197], v[78:81]
	v_addc_co_u32_e32 v153, vcc, 0, v209, vcc
	global_store_dword v[152:153], v192, off
	global_store_dword v[150:151], v88, off
	global_store_dword v[152:153], v193, off offset:2048
	global_store_dword v[150:151], v89, off offset:2048
	v_add_u32_e32 v3, v207, v182
	v_add_u32_e32 v4, v199, v176
	v_mfma_f32_16x16x32_bf16 v[74:77], v[74:77], v[194:197], v[82:85]
	v_add_u32_e32 v2, s92, v181
	ds_read_b128 v[190:193], v3 offset:17664
	ds_read_b128 v[194:197], v2 offset:39104
	ds_read_b128 v[86:89], v4 offset:27904
	v_add_u32_e32 v4, v198, v176
	ds_read_b128 v[198:201], v3 offset:18944
	ds_read_b128 v[202:205], v2 offset:39168
	ds_read_b128 v[82:85], v4 offset:27904
	s_waitcnt lgkmcnt(4)
	v_pk_mul_f32 v[64:65], v[64:65], v[196:197]
	v_pk_mul_f32 v[62:63], v[62:63], v[194:195]
	v_pk_mul_f32 v[36:37], v[36:37], v[196:197]
	v_pk_mul_f32 v[34:35], v[34:35], v[194:195]
	global_store_dword v[208:209], v78, off offset:64
	s_waitcnt lgkmcnt(1)
	v_pk_mul_f32 v[68:69], v[68:69], v[204:205]
	v_pk_mul_f32 v[66:67], v[66:67], v[202:203]
	v_pk_mul_f32 v[32:33], v[32:33], v[204:205]
	v_pk_mul_f32 v[30:31], v[30:31], v[202:203]
	v_mfma_f32_16x16x32_bf16 v[62:65], v[190:193], v[86:89], v[62:65]
	s_andn2_b64 vcc, exec, s[90:91]
	s_mov_b32 s92, 8
	s_waitcnt lgkmcnt(0)
	v_mfma_f32_16x16x32_bf16 v[34:37], v[190:193], v[82:85], v[34:37]
	ds_read_b128 v[190:193], v3 offset:20224
	ds_read_b128 v[194:197], v2 offset:39232
	ds_read_b128 v[202:205], v2 offset:39296
	global_store_dword v[154:155], v74, off offset:64
	v_mfma_f32_16x16x32_bf16 v[66:69], v[198:201], v[86:89], v[66:69]
	global_store_dword v[208:209], v79, off offset:2112
	s_waitcnt lgkmcnt(1)
	v_pk_mul_f32 v[56:57], v[56:57], v[196:197]
	v_pk_mul_f32 v[54:55], v[54:55], v[194:195]
	v_mfma_f32_16x16x32_bf16 v[30:33], v[198:201], v[82:85], v[30:33]
	ds_read_b128 v[198:201], v3 offset:21504
	v_pk_mul_f32 v[28:29], v[28:29], v[196:197]
	v_pk_mul_f32 v[26:27], v[26:27], v[194:195]
	s_waitcnt lgkmcnt(1)
	v_pk_mul_f32 v[60:61], v[60:61], v[204:205]
	v_pk_mul_f32 v[58:59], v[58:59], v[202:203]
	v_pk_mul_f32 v[24:25], v[24:25], v[204:205]
	v_pk_mul_f32 v[22:23], v[22:23], v[202:203]
	v_mfma_f32_16x16x32_bf16 v[54:57], v[190:193], v[86:89], v[54:57]
	v_mfma_f32_16x16x32_bf16 v[26:29], v[190:193], v[82:85], v[26:29]
	ds_read_b128 v[190:193], v3 offset:22784
	ds_read_b128 v[194:197], v2 offset:39360
	ds_read_b128 v[202:205], v2 offset:39424
	global_store_dword v[154:155], v75, off offset:2112
	s_waitcnt lgkmcnt(3)
	v_mfma_f32_16x16x32_bf16 v[58:61], v[198:201], v[86:89], v[58:61]
	global_store_dword v[152:153], v80, off offset:64
	s_waitcnt lgkmcnt(1)
	v_pk_mul_f32 v[48:49], v[48:49], v[196:197]
	v_pk_mul_f32 v[46:47], v[46:47], v[194:195]
	v_mfma_f32_16x16x32_bf16 v[22:25], v[198:201], v[82:85], v[22:25]
	ds_read_b128 v[198:201], v3 offset:24064
	v_pk_mul_f32 v[20:21], v[20:21], v[196:197]
	v_pk_mul_f32 v[18:19], v[18:19], v[194:195]
	s_waitcnt lgkmcnt(1)
	v_pk_mul_f32 v[52:53], v[52:53], v[204:205]
	v_pk_mul_f32 v[50:51], v[50:51], v[202:203]
	v_pk_mul_f32 v[16:17], v[16:17], v[204:205]
	v_pk_mul_f32 v[14:15], v[14:15], v[202:203]
	v_mfma_f32_16x16x32_bf16 v[46:49], v[190:193], v[86:89], v[46:49]
	v_mfma_f32_16x16x32_bf16 v[18:21], v[190:193], v[82:85], v[18:21]
	ds_read_b128 v[190:193], v3 offset:25344
	ds_read_b128 v[194:197], v2 offset:39488
	ds_read_b128 v[202:205], v2 offset:39552
	global_store_dword v[150:151], v76, off offset:64
	s_waitcnt lgkmcnt(3)
	v_mfma_f32_16x16x32_bf16 v[50:53], v[198:201], v[86:89], v[50:53]
	global_store_dword v[152:153], v81, off offset:2112
	s_waitcnt lgkmcnt(1)
	v_pk_mul_f32 v[40:41], v[40:41], v[196:197]
	v_pk_mul_f32 v[38:39], v[38:39], v[194:195]
	v_mfma_f32_16x16x32_bf16 v[14:17], v[198:201], v[82:85], v[14:17]
	ds_read_b128 v[198:201], v3 offset:26624
	v_pk_mul_f32 v[12:13], v[12:13], v[196:197]
	v_pk_mul_f32 v[10:11], v[10:11], v[194:195]
	s_waitcnt lgkmcnt(1)
	v_pk_mul_f32 v[44:45], v[44:45], v[204:205]
	v_pk_mul_f32 v[42:43], v[42:43], v[202:203]
	v_pk_mul_f32 v[8:9], v[8:9], v[204:205]
	v_pk_mul_f32 v[6:7], v[6:7], v[202:203]
	v_mfma_f32_16x16x32_bf16 v[38:41], v[190:193], v[86:89], v[38:41]
	global_store_dword v[150:151], v77, off offset:2112
	v_mfma_f32_16x16x32_bf16 v[10:13], v[190:193], v[82:85], v[10:13]
	s_waitcnt lgkmcnt(0)
	v_mfma_f32_16x16x32_bf16 v[42:45], v[198:201], v[86:89], v[42:45]
	v_mfma_f32_16x16x32_bf16 v[6:9], v[198:201], v[82:85], v[6:9]
	s_cbranch_vccnz .LBB0_474
	s_waitcnt vmcnt(31)
	v_lshlrev_b32_e32 v2, 16, v119
	v_add_f32_e32 v4, 0, v2
	s_waitcnt vmcnt(29)
	v_lshlrev_b32_e32 v2, 16, v123
	v_add_f32_e32 v80, v4, v2
	s_waitcnt vmcnt(27)
	v_lshlrev_b32_e32 v2, 16, v127
	v_add_f32_e32 v82, v80, v2
	s_waitcnt vmcnt(25)
	v_lshlrev_b32_e32 v2, 16, v131
	v_add_f32_e32 v84, v82, v2
	s_waitcnt vmcnt(23)
	v_lshlrev_b32_e32 v2, 16, v135
	v_add_f32_e32 v86, v84, v2
	s_waitcnt vmcnt(21)
	v_lshlrev_b32_e32 v2, 16, v139
	v_add_f32_e32 v88, v86, v2
	s_waitcnt vmcnt(19)
	v_lshlrev_b32_e32 v2, 16, v187
	v_add_f32_e32 v150, v88, v2
	s_waitcnt vmcnt(17)
	v_lshlrev_b32_e32 v2, 16, v189
	v_add_f32_e32 v152, v150, v2
	ds_bpermute_b32 v2, v91, v152
	ds_bpermute_b32 v74, v93, v152
	ds_bpermute_b32 v3, v95, v152
	ds_bpermute_b32 v75, v97, v152
	s_add_i32 s92, s33, 1
	s_waitcnt lgkmcnt(3)
	v_cndmask_b32_e64 v76, v2, 0, s[4:5]
	s_waitcnt lgkmcnt(2)
	v_cndmask_b32_e64 v77, 0, v74, s[6:7]
	v_add_f32_e32 v76, v76, v77
	s_waitcnt lgkmcnt(1)
	v_cndmask_b32_e64 v77, 0, v3, s[8:9]
	v_add_f32_e32 v153, v76, v77
	s_waitcnt lgkmcnt(0)
	v_pk_add_f32 v[2:3], v[2:3], v[74:75]
	v_mul_f32_e32 v74, 0x3fb8aa3b, v153
	v_add_f32_e32 v4, v4, v153
	v_exp_f32_e32 v74, v74
	v_mul_f32_e32 v4, 0x3fb8aa3b, v4
	v_exp_f32_e32 v76, v4
	v_add_f32_e32 v3, v2, v3
	v_rcp_f32_e32 v74, v74
	v_mul_f32_e32 v2, 0x3fb8aa3b, v115
	v_rcp_f32_e32 v77, v76
	s_bitcmp1_b32 s92, 0
	v_exp_f32_e32 v154, v2
	s_cselect_b32 s90, 0x9ac0, 0
	v_fma_f32 v75, -v74, v76, 1.0
	v_lshlrev_b32_e32 v74, 16, v117
	s_add_i32 s93, s90, 0
	v_pk_mul_f32 v[74:75], v[76:77], v[74:75]
	v_lshl_add_u32 v76, v99, 1, s93
	v_cvt_pk_bf16_f32 v4, v74, v75
	ds_write_b16 v76, v4
	ds_write_b16_d16_hi v76, v4 offset:8832
	v_mul_f32_e32 v4, v154, v74
	s_lshl_b32 s90, s92, 5
	v_cvt_pk_bf16_f32 v74, v4, v4
	s_lshl_b32 s98, s90, 10
	s_mov_b32 s99, 0
	v_lshl_add_u64 v[78:79], v[240:241], 0, s[98:99]
	v_add_f32_e32 v4, v80, v153
	v_mul_f32_e32 v4, 0x3fb8aa3b, v4
	global_store_short_d16_hi v[78:79], v74, off
	v_exp_f32_e32 v78, v4
	v_lshlrev_b32_e32 v76, 16, v121
	v_lshl_add_u32 v74, v103, 1, s93
	v_mul_f32_e32 v2, 0x3fb8aa3b, v3
	v_rcp_f32_e32 v79, v78
	v_fma_f32 v77, -v78, v77, 1.0
	v_exp_f32_e32 v2, v2
	v_pk_mul_f32 v[76:77], v[78:79], v[76:77]
	s_nop 0
	v_cvt_pk_bf16_f32 v4, v76, v77
	ds_write_b16 v74, v4
	ds_write_b16_d16_hi v74, v4 offset:8832
	v_mul_f32_e32 v4, v154, v76
	v_cvt_pk_bf16_f32 v74, v4, v4
	v_lshl_add_u64 v[80:81], v[242:243], 0, s[98:99]
	v_add_f32_e32 v4, v82, v153
	v_mul_f32_e32 v4, 0x3fb8aa3b, v4
	global_store_short_d16_hi v[80:81], v74, off
	v_exp_f32_e32 v80, v4
	v_lshlrev_b32_e32 v78, 16, v125
	v_lshl_add_u32 v74, v156, 1, s93
	v_rcp_f32_e32 v81, v80
	v_fma_f32 v79, -v80, v79, 1.0
	v_pk_mul_f32 v[78:79], v[80:81], v[78:79]
	s_nop 0
	v_cvt_pk_bf16_f32 v4, v78, v79
	ds_write_b16 v74, v4
	ds_write_b16_d16_hi v74, v4 offset:8832
	v_mul_f32_e32 v4, v154, v78
	v_cvt_pk_bf16_f32 v74, v4, v4
	v_lshl_add_u64 v[82:83], v[244:245], 0, s[98:99]
	v_add_f32_e32 v4, v84, v153
	v_mul_f32_e32 v4, 0x3fb8aa3b, v4
	global_store_short_d16_hi v[82:83], v74, off
	v_exp_f32_e32 v82, v4
	v_lshlrev_b32_e32 v80, 16, v129
	v_lshl_add_u32 v74, v158, 1, s93
	v_mov_b32_e32 v78, v75
	v_rcp_f32_e32 v83, v82
	v_fma_f32 v81, -v82, v81, 1.0
	v_pk_mul_f32 v[80:81], v[82:83], v[80:81]
	s_nop 0
	v_cvt_pk_bf16_f32 v4, v80, v81
	ds_write_b16 v74, v4
	ds_write_b16_d16_hi v74, v4 offset:8832
	v_mul_f32_e32 v4, v154, v80
	v_cvt_pk_bf16_f32 v74, v4, v4
	v_lshl_add_u64 v[84:85], v[246:247], 0, s[98:99]
	v_add_f32_e32 v4, v86, v153
	v_mul_f32_e32 v4, 0x3fb8aa3b, v4
	global_store_short_d16_hi v[84:85], v74, off
	v_exp_f32_e32 v84, v4
	v_lshlrev_b32_e32 v82, 16, v133
	v_lshl_add_u32 v74, v160, 1, s93
	v_mov_b32_e32 v80, v77
	v_rcp_f32_e32 v85, v84
	v_fma_f32 v83, -v84, v83, 1.0
	v_pk_mul_f32 v[76:77], v[2:3], v[80:81] op_sel_hi:[0,1]
	v_pk_mul_f32 v[82:83], v[84:85], v[82:83]
	s_nop 0
	v_cvt_pk_bf16_f32 v4, v82, v83
	ds_write_b16 v74, v4
	ds_write_b16_d16_hi v74, v4 offset:8832
	v_mul_f32_e32 v4, v154, v82
	v_cvt_pk_bf16_f32 v74, v4, v4
	v_lshl_add_u64 v[86:87], v[248:249], 0, s[98:99]
	v_add_f32_e32 v4, v88, v153
	v_mul_f32_e32 v4, 0x3fb8aa3b, v4
	global_store_short_d16_hi v[86:87], v74, off
	v_exp_f32_e32 v86, v4
	v_lshlrev_b32_e32 v84, 16, v137
	v_lshl_add_u32 v74, v162, 1, s93
	v_rcp_f32_e32 v87, v86
	v_fma_f32 v85, -v86, v85, 1.0
	v_pk_mul_f32 v[84:85], v[86:87], v[84:85]
	s_nop 0
	v_cvt_pk_bf16_f32 v4, v84, v85
	ds_write_b16 v74, v4
	ds_write_b16_d16_hi v74, v4 offset:8832
	v_mul_f32_e32 v4, v154, v84
	v_cvt_pk_bf16_f32 v74, v4, v4
	v_lshl_add_u64 v[88:89], v[250:251], 0, s[98:99]
	v_add_f32_e32 v4, v150, v153
	v_mul_f32_e32 v4, 0x3fb8aa3b, v4
	global_store_short_d16_hi v[88:89], v74, off
	v_exp_f32_e32 v88, v4
	v_lshlrev_b32_e32 v86, 16, v141
	v_lshl_add_u32 v74, v164, 1, s93
	v_bfe_u32 v84, v76, 16, 1
	v_rcp_f32_e32 v89, v88
	v_fma_f32 v87, -v88, v87, 1.0
	v_add3_u32 v84, v76, v84, s96
	v_pk_mul_f32 v[86:87], v[88:89], v[86:87]
	s_nop 0
	v_cvt_pk_bf16_f32 v4, v86, v87
	ds_write_b16 v74, v4
	ds_write_b16_d16_hi v74, v4 offset:8832
	v_mul_f32_e32 v4, v154, v86
	v_cvt_pk_bf16_f32 v74, v4, v4
	v_lshl_add_u64 v[150:151], v[252:253], 0, s[98:99]
	v_add_f32_e32 v4, v152, v153
	v_mul_f32_e32 v4, 0x3fb8aa3b, v4
	global_store_short_d16_hi v[150:151], v74, off
	v_exp_f32_e32 v150, v4
	v_lshlrev_b32_e32 v88, 16, v188
	v_lshl_add_u32 v74, v166, 1, s93
	v_mov_b32_e32 v86, v83
	v_rcp_f32_e32 v151, v150
	v_fma_f32 v89, -v150, v89, 1.0
	v_bfe_u32 v83, v77, 16, 1
	v_add3_u32 v83, v77, v83, s96
	v_pk_mul_f32 v[88:89], v[150:151], v[88:89]
	s_nop 0
	v_cvt_pk_bf16_f32 v4, v88, v89
	ds_write_b16 v74, v4
	ds_write_b16_d16_hi v74, v4 offset:8832
	v_mul_f32_e32 v4, v154, v88
	v_cvt_pk_bf16_f32 v74, v4, v4
	v_lshl_add_u64 v[150:151], v[254:255], 0, s[98:99]
	v_mov_b32_e32 v88, v85
	v_pk_mul_f32 v[80:81], v[2:3], v[88:89] op_sel_hi:[0,1]
	global_store_short_d16_hi v[150:151], v74, off
	v_pk_mul_f32 v[74:75], v[2:3], v[78:79] op_sel_hi:[0,1]
	v_pk_mul_f32 v[78:79], v[2:3], v[86:87] op_sel_hi:[0,1]
	v_bfe_u32 v82, v80, 16, 1
	v_bfe_u32 v4, v81, 16, 1
	v_add3_u32 v76, v80, v82, s96
	v_bfe_u32 v82, v79, 16, 1
	v_add3_u32 v4, v81, v4, s96
	v_bfe_u32 v77, v74, 16, 1
	v_bfe_u32 v80, v75, 16, 1
	v_bfe_u32 v81, v78, 16, 1
	v_add3_u32 v79, v79, v82, s96
	v_add3_u32 v78, v78, v81, s96
	v_add3_u32 v75, v75, v80, s96
	v_add3_u32 v74, v74, v77, s96
	v_lshrrev_b32_e32 v77, 16, v79
	v_lshrrev_b32_e32 v74, 16, v74
	v_lshrrev_b32_e32 v75, 16, v75
	v_lshrrev_b32_e32 v78, 16, v78
	v_and_or_b32 v77, v4, s97, v77
	v_lshl_add_u32 v4, v168, 1, s93
	v_and_or_b32 v76, v76, s97, v78
	v_and_or_b32 v75, v83, s97, v75
	v_and_or_b32 v74, v84, s97, v74
	v_lshl_add_u32 v78, v90, 1, v4
	ds_write_b128 v78, v[74:77] offset:17664
	s_and_saveexec_b64 s[90:91], s[4:5]
	v_add_u32_e32 v4, v4, v183
	ds_write_b32 v4, v2 offset:39104
	s_or_b64 exec, exec, s[90:91]
	v_add_u32_e32 v2, s93, v170
	v_add3_u32 v2, v2, v171, v172
	s_cmp_gt_u32 s33, 5
	s_waitcnt vmcnt(24)
	ds_write_b16 v2, v70 offset:27904
	ds_write_b16_d16_hi v2, v70 offset:27984
	ds_write_b16 v2, v71 offset:28064
	ds_write_b16_d16_hi v2, v71 offset:28144
	ds_write_b16 v2, v72 offset:28224
	ds_write_b16_d16_hi v2, v72 offset:28304
	ds_write_b16 v2, v73 offset:28384
	ds_write_b16_d16_hi v2, v73 offset:28464
	s_cbranch_scc1 .LBB0_473
	s_add_i32 s16, s16, 64
	v_or_b32_e32 v2, s16, v90
	v_mul_lo_u32 v4, v2, s63
	v_lshl_add_u64 v[70:71], v[4:5], 1, v[142:143]
	v_add_co_u32_e32 v72, vcc, 0x1000, v70
	global_load_ushort v117, v[70:71], off
	global_load_ushort v119, v[70:71], off offset:1024
	v_addc_co_u32_e32 v73, vcc, 0, v71, vcc
	global_load_ushort v121, v[72:73], off offset:1536
	global_load_ushort v123, v[72:73], off offset:2560
	v_add_co_u32_e32 v72, vcc, 0x2000, v70
	v_or_b32_e32 v2, s16, v1
	s_nop 0
	v_addc_co_u32_e32 v73, vcc, 0, v71, vcc
	global_load_ushort v125, v[72:73], off offset:3072
	v_add_co_u32_e32 v72, vcc, 0x3000, v70
	v_mul_lo_u32 v4, v2, s63
	s_nop 0
	v_addc_co_u32_e32 v73, vcc, 0, v71, vcc
	global_load_ushort v127, v[72:73], off
	v_add_co_u32_e32 v72, vcc, 0x4000, v70
	s_nop 1
	v_addc_co_u32_e32 v73, vcc, 0, v71, vcc
	global_load_ushort v129, v[72:73], off offset:512
	global_load_ushort v131, v[72:73], off offset:1536
	v_add_co_u32_e32 v72, vcc, 0x5000, v70
	s_nop 1
	v_addc_co_u32_e32 v73, vcc, 0, v71, vcc
	global_load_ushort v133, v[72:73], off offset:2048
	global_load_ushort v135, v[72:73], off offset:3072
	v_add_co_u32_e32 v72, vcc, 0x6000, v70
	s_nop 1
	v_addc_co_u32_e32 v73, vcc, 0, v71, vcc
	global_load_ushort v137, v[72:73], off offset:3584
	v_add_co_u32_e32 v72, vcc, 0x7000, v70
	s_nop 1
	v_addc_co_u32_e32 v73, vcc, 0, v71, vcc
	global_load_ushort v139, v[72:73], off offset:512
	v_add_co_u32_e32 v72, vcc, 0x8000, v70
	s_nop 1
	v_addc_co_u32_e32 v73, vcc, 0, v71, vcc
	v_add_co_u32_e32 v70, vcc, 0x9000, v70
	global_load_ushort v141, v[72:73], off offset:1024
	global_load_ushort v187, v[72:73], off offset:2048
	v_addc_co_u32_e32 v71, vcc, 0, v71, vcc
	global_load_ushort v188, v[70:71], off offset:2560
	global_load_ushort v189, v[70:71], off offset:3584
	v_lshl_add_u64 v[70:71], v[4:5], 1, v[144:145]
	global_load_dwordx4 v[70:73], v[70:71], off offset:2048
